# attention ctx pass: the 64 per-score SC multiplies that only fed the running max are replaced by max over raw scores then one multiply (bit-identical, monotone rounding)
# speedup vs baseline: 1.0041x; 1.0041x over previous
.Lqjoin_299:
	ds_read_b128 v[8:11], v132
	ds_read_b128 v[12:15], v132 offset:512
	ds_read_b128 v[16:19], v133
	ds_read_b128 v[20:23], v133 offset:512
	ds_read_b128 v[24:27], v132 offset:4096
	ds_read_b128 v[28:31], v132 offset:4608
	ds_read_b128 v[32:35], v133 offset:4096
	ds_read_b128 v[36:39], v133 offset:4608
	s_waitcnt vmcnt(1) lgkmcnt(7)
	v_mfma_f32_16x16x32_bf16 v[8:11], v[8:11], v[4:7], 0
	s_waitcnt vmcnt(0) lgkmcnt(5)
	v_mfma_f32_16x16x32_bf16 v[68:71], v[16:19], v[0:3], v[8:11]
	v_mfma_f32_16x16x32_bf16 v[8:11], v[12:15], v[4:7], 0
	s_waitcnt lgkmcnt(4)
	v_mfma_f32_16x16x32_bf16 v[64:67], v[20:23], v[0:3], v[8:11]
	s_nop 4
	ds_read_b128 v[8:11], v132 offset:8192
	ds_read_b128 v[12:15], v132 offset:8704
	ds_read_b128 v[16:19], v133 offset:8192
	ds_read_b128 v[20:23], v133 offset:8704
	s_waitcnt lgkmcnt(7)
	v_mfma_f32_16x16x32_bf16 v[24:27], v[24:27], v[4:7], 0
	s_waitcnt lgkmcnt(5)
	v_mfma_f32_16x16x32_bf16 v[60:63], v[32:35], v[0:3], v[24:27]
	v_mfma_f32_16x16x32_bf16 v[24:27], v[28:31], v[4:7], 0
	s_waitcnt lgkmcnt(4)
	v_mfma_f32_16x16x32_bf16 v[56:59], v[36:39], v[0:3], v[24:27]
	s_nop 4
	ds_read_b128 v[24:27], v132 offset:12288
	ds_read_b128 v[28:31], v132 offset:12800
	ds_read_b128 v[32:35], v133 offset:12288
	ds_read_b128 v[36:39], v133 offset:12800
	s_waitcnt lgkmcnt(7)
	v_mfma_f32_16x16x32_bf16 v[8:11], v[8:11], v[4:7], 0
	s_waitcnt lgkmcnt(5)
	v_mfma_f32_16x16x32_bf16 v[52:55], v[16:19], v[0:3], v[8:11]
	v_mfma_f32_16x16x32_bf16 v[8:11], v[12:15], v[4:7], 0
	s_waitcnt lgkmcnt(4)
	v_mfma_f32_16x16x32_bf16 v[48:51], v[20:23], v[0:3], v[8:11]
	s_nop 4
	ds_read_b128 v[8:11], v132 offset:16384
	ds_read_b128 v[12:15], v132 offset:16896
	ds_read_b128 v[16:19], v133 offset:16384
	ds_read_b128 v[20:23], v133 offset:16896
	s_waitcnt lgkmcnt(7)
	v_mfma_f32_16x16x32_bf16 v[24:27], v[24:27], v[4:7], 0
	s_waitcnt lgkmcnt(5)
	v_mfma_f32_16x16x32_bf16 v[44:47], v[32:35], v[0:3], v[24:27]
	v_mfma_f32_16x16x32_bf16 v[24:27], v[28:31], v[4:7], 0
	s_waitcnt lgkmcnt(4)
	v_mfma_f32_16x16x32_bf16 v[40:43], v[36:39], v[0:3], v[24:27]
	s_nop 4
	ds_read_b128 v[24:27], v132 offset:20480
	ds_read_b128 v[152:155], v132 offset:20992
	ds_read_b128 v[28:31], v133 offset:20480
	ds_read_b128 v[170:173], v133 offset:20992
	s_waitcnt lgkmcnt(7)
	v_mfma_f32_16x16x32_bf16 v[8:11], v[8:11], v[4:7], 0
	s_waitcnt lgkmcnt(5)
	v_mfma_f32_16x16x32_bf16 v[36:39], v[16:19], v[0:3], v[8:11]
	v_mfma_f32_16x16x32_bf16 v[8:11], v[12:15], v[4:7], 0
	s_waitcnt lgkmcnt(4)
	v_mfma_f32_16x16x32_bf16 v[32:35], v[20:23], v[0:3], v[8:11]
	s_nop 4
	ds_read_b128 v[8:11], v132 offset:24576
	ds_read_b128 v[12:15], v132 offset:25088
	ds_read_b128 v[16:19], v133 offset:24576
	ds_read_b128 v[174:177], v133 offset:25088
	s_waitcnt lgkmcnt(7)
	v_mfma_f32_16x16x32_bf16 v[20:23], v[24:27], v[4:7], 0
	s_waitcnt lgkmcnt(5)
	v_mfma_f32_16x16x32_bf16 v[28:31], v[28:31], v[0:3], v[20:23]
	v_mfma_f32_16x16x32_bf16 v[20:23], v[152:155], v[4:7], 0
	s_waitcnt lgkmcnt(4)
	v_mfma_f32_16x16x32_bf16 v[24:27], v[170:173], v[0:3], v[20:23]
	s_nop 4
	ds_read_b128 v[152:155], v132 offset:28672
	ds_read_b128 v[170:173], v132 offset:29184
	ds_read_b128 v[178:181], v133 offset:28672
	ds_read_b128 v[182:185], v133 offset:29184
	s_waitcnt lgkmcnt(7)
	v_mfma_f32_16x16x32_bf16 v[8:11], v[8:11], v[4:7], 0
	s_waitcnt lgkmcnt(5)
	v_mfma_f32_16x16x32_bf16 v[20:23], v[16:19], v[0:3], v[8:11]
	v_mfma_f32_16x16x32_bf16 v[8:11], v[12:15], v[4:7], 0
	s_waitcnt lgkmcnt(4)
	v_mfma_f32_16x16x32_bf16 v[16:19], v[174:177], v[0:3], v[8:11]
	s_nop 4
	s_waitcnt lgkmcnt(3)
	v_mfma_f32_16x16x32_bf16 v[8:11], v[152:155], v[4:7], 0
	s_waitcnt lgkmcnt(1)
	v_mfma_f32_16x16x32_bf16 v[12:15], v[178:181], v[0:3], v[8:11]
	v_mfma_f32_16x16x32_bf16 v[8:11], v[170:173], v[4:7], 0
	s_waitcnt lgkmcnt(0)
	v_mfma_f32_16x16x32_bf16 v[8:11], v[182:185], v[0:3], v[8:11]
	s_nop 4
	s_mov_b32 s30, 0xff800000
	v_max3_f32 v97, v68, s30, v69
	v_max3_f32 v97, v97, v70, v71
	v_max3_f32 v97, v97, v64, v65
	v_max3_f32 v97, v97, v66, v67
	v_max3_f32 v97, v97, v60, v61
	v_max3_f32 v97, v97, v62, v63
	v_max3_f32 v97, v97, v56, v57
	v_max3_f32 v97, v97, v58, v59
	v_max3_f32 v97, v97, v52, v53
	v_max3_f32 v97, v97, v54, v55
	v_max3_f32 v97, v97, v48, v49
	v_max3_f32 v97, v97, v50, v51
	v_max3_f32 v97, v97, v44, v45
	v_max3_f32 v97, v97, v46, v47
	v_max3_f32 v97, v97, v40, v41
	v_max3_f32 v97, v97, v42, v43
	v_max3_f32 v97, v97, v36, v37
	v_max3_f32 v97, v97, v38, v39
	v_max3_f32 v97, v97, v32, v33
	v_max3_f32 v97, v97, v34, v35
	v_max3_f32 v97, v97, v28, v29
	v_max3_f32 v97, v97, v30, v31
	v_max3_f32 v97, v97, v24, v25
	v_max3_f32 v97, v97, v26, v27
	v_max3_f32 v97, v97, v20, v21
	v_max3_f32 v97, v97, v22, v23
	v_max3_f32 v97, v97, v16, v17
	v_max3_f32 v97, v97, v18, v19
	v_max3_f32 v97, v97, v12, v13
	v_max3_f32 v97, v97, v14, v15
	v_max3_f32 v97, v97, v8, v9
	v_max3_f32 v97, v97, v10, v11
	v_mul_f32_e32 v97, 0x3e38aa3b, v97
	ds_bpermute_b32 v99, v114, v97
	ds_read_b128 v[152:155], v134 offset:32768
	ds_read_b128 v[170:173], v134 offset:40960
	ds_read_b128 v[174:177], v134 offset:49152
	ds_read_b128 v[178:181], v134 offset:57344
	ds_read_b128 v[182:185], v135 offset:32768
	ds_read_b128 v[186:189], v135 offset:40960
	ds_read_b128 v[190:193], v135 offset:49152
	ds_read_b128 v[194:197], v135 offset:57344
	s_waitcnt lgkmcnt(8)
	v_max_f32_e32 v99, v99, v99
	v_max_f32_e32 v97, v97, v99
	ds_bpermute_b32 v99, v115, v97
	s_waitcnt lgkmcnt(0)
	v_max_f32_e32 v99, v99, v99
	v_max_f32_e32 v97, v97, v99
	v_sub_f32_e32 v99, 0xff800000, v97
	v_exp_f32_e32 v99, v99
	s_nop 0
	v_mul_f32_e32 v198, 0, v99
	v_mov_b32_e32 v199, v198
	v_mov_b32_e32 v200, v198
	v_mov_b32_e32 v201, v198
	v_fma_f32 v68, v68, s67, -v97
	v_exp_f32_e32 v68, v68
	v_fma_f32 v69, v69, s67, -v97
	v_exp_f32_e32 v69, v69
	v_fma_f32 v70, v70, s67, -v97
	v_exp_f32_e32 v70, v70
	v_fma_f32 v71, v71, s67, -v97
	v_exp_f32_e32 v71, v71
	v_fma_f32 v64, v64, s67, -v97
	v_fma_f32 v99, 0, v99, v68
	v_exp_f32_e32 v105, v64
	v_add_f32_e32 v99, v69, v99
	v_add_f32_e32 v99, v70, v99
	v_add_f32_e32 v99, v71, v99
	v_fma_f32 v65, v65, s67, -v97
	v_add_f32_e32 v64, v105, v99
	v_exp_f32_e32 v99, v65
	v_fma_f32 v65, v66, s67, -v97
	v_exp_f32_e32 v151, v65
	v_fma_f32 v65, v67, s67, -v97
	v_exp_f32_e32 v67, v65
	v_add_f32_e32 v64, v99, v64
	v_add_f32_e32 v64, v151, v64
	v_cvt_pk_bf16_f32 v65, v70, v71
	v_add_f32_e32 v160, v67, v64
	v_cvt_pk_bf16_f32 v64, v68, v69
	v_cvt_pk_bf16_f32 v66, v105, v99
	v_cvt_pk_bf16_f32 v67, v151, v67
	s_nop 1
	v_mfma_f32_16x16x32_bf16 v[68:71], v[152:155], v[64:67], v[198:201]
	v_mfma_f32_16x16x32_bf16 v[152:155], v[170:173], v[64:67], v[198:201]
	v_mfma_f32_16x16x32_bf16 v[170:173], v[174:177], v[64:67], v[198:201]
	v_mfma_f32_16x16x32_bf16 v[64:67], v[178:181], v[64:67], v[198:201]
	ds_read_b128 v[174:177], v136 offset:32768
	ds_read_b128 v[178:181], v136 offset:40960
	s_nop 0
	ds_read_b128 v[198:201], v136 offset:49152
	ds_read_b128 v[202:205], v136 offset:57344
	v_fma_f32 v60, v60, s67, -v97
	v_exp_f32_e32 v60, v60
	v_fma_f32 v61, v61, s67, -v97
	v_exp_f32_e32 v61, v61
	v_fma_f32 v62, v62, s67, -v97
	v_exp_f32_e32 v62, v62
	v_fma_f32 v63, v63, s67, -v97
	v_exp_f32_e32 v63, v63
	v_fma_f32 v56, v56, s67, -v97
	v_add_f32_e32 v99, v60, v160
	v_exp_f32_e32 v105, v56
	v_add_f32_e32 v99, v61, v99
	v_add_f32_e32 v99, v62, v99
	v_add_f32_e32 v99, v63, v99
	v_fma_f32 v57, v57, s67, -v97
	v_add_f32_e32 v56, v105, v99
	v_exp_f32_e32 v99, v57
	v_fma_f32 v57, v58, s67, -v97
	v_exp_f32_e32 v151, v57
	v_fma_f32 v57, v59, s67, -v97
	v_exp_f32_e32 v59, v57
	v_add_f32_e32 v56, v99, v56
	v_add_f32_e32 v56, v151, v56
	v_cvt_pk_bf16_f32 v57, v62, v63
	v_add_f32_e32 v160, v59, v56
	v_cvt_pk_bf16_f32 v56, v60, v61
	v_cvt_pk_bf16_f32 v58, v105, v99
	v_cvt_pk_bf16_f32 v59, v151, v59
	s_nop 1
	v_mfma_f32_16x16x32_bf16 v[60:63], v[182:185], v[56:59], v[68:71]
	v_mfma_f32_16x16x32_bf16 v[68:71], v[186:189], v[56:59], v[152:155]
	v_mfma_f32_16x16x32_bf16 v[152:155], v[190:193], v[56:59], v[170:173]
	v_mfma_f32_16x16x32_bf16 v[56:59], v[194:197], v[56:59], v[64:67]
	s_nop 2
	ds_read_b128 v[64:67], v137 offset:32768
	ds_read_b128 v[170:173], v137 offset:40960
	ds_read_b128 v[182:185], v137 offset:49152
	ds_read_b128 v[186:189], v137 offset:57344
	v_fma_f32 v52, v52, s67, -v97
	v_exp_f32_e32 v52, v52
	v_fma_f32 v53, v53, s67, -v97
	v_exp_f32_e32 v53, v53
	v_fma_f32 v54, v54, s67, -v97
	v_exp_f32_e32 v54, v54
	v_fma_f32 v55, v55, s67, -v97
	v_exp_f32_e32 v55, v55
	v_fma_f32 v48, v48, s67, -v97
	v_add_f32_e32 v99, v52, v160
	v_exp_f32_e32 v105, v48
	v_add_f32_e32 v99, v53, v99
	v_add_f32_e32 v99, v54, v99
	v_add_f32_e32 v99, v55, v99
	v_fma_f32 v49, v49, s67, -v97
	v_add_f32_e32 v48, v105, v99
	v_exp_f32_e32 v99, v49
	v_fma_f32 v49, v50, s67, -v97
	v_exp_f32_e32 v151, v49
	v_fma_f32 v49, v51, s67, -v97
	v_exp_f32_e32 v51, v49
	v_add_f32_e32 v48, v99, v48
	v_add_f32_e32 v48, v151, v48
	v_cvt_pk_bf16_f32 v49, v54, v55
	v_add_f32_e32 v160, v51, v48
	v_cvt_pk_bf16_f32 v48, v52, v53
	v_cvt_pk_bf16_f32 v50, v105, v99
	v_cvt_pk_bf16_f32 v51, v151, v51
	s_waitcnt lgkmcnt(7)
	s_nop 0
	v_mfma_f32_16x16x32_bf16 v[52:55], v[174:177], v[48:51], v[60:63]
	s_waitcnt lgkmcnt(6)
	v_mfma_f32_16x16x32_bf16 v[60:63], v[178:181], v[48:51], v[68:71]
	s_waitcnt lgkmcnt(5)
	v_mfma_f32_16x16x32_bf16 v[68:71], v[198:201], v[48:51], v[152:155]
	s_waitcnt lgkmcnt(4)
	v_mfma_f32_16x16x32_bf16 v[48:51], v[202:205], v[48:51], v[56:59]
	s_nop 2
	ds_read_b128 v[56:59], v138 offset:32768
	ds_read_b128 v[152:155], v138 offset:40960
	ds_read_b128 v[174:177], v138 offset:49152
	ds_read_b128 v[178:181], v138 offset:57344
	v_fma_f32 v44, v44, s67, -v97
	v_exp_f32_e32 v44, v44
	v_fma_f32 v45, v45, s67, -v97
	v_exp_f32_e32 v45, v45
	v_fma_f32 v46, v46, s67, -v97
	v_exp_f32_e32 v46, v46
	v_fma_f32 v47, v47, s67, -v97
	v_exp_f32_e32 v47, v47
	v_fma_f32 v40, v40, s67, -v97
	v_add_f32_e32 v99, v44, v160
	v_exp_f32_e32 v105, v40
	v_add_f32_e32 v99, v45, v99
	v_add_f32_e32 v99, v46, v99
	v_add_f32_e32 v99, v47, v99
	v_fma_f32 v41, v41, s67, -v97
	v_add_f32_e32 v40, v105, v99
	v_exp_f32_e32 v99, v41
	v_fma_f32 v41, v42, s67, -v97
	v_exp_f32_e32 v151, v41
	v_fma_f32 v41, v43, s67, -v97
	v_exp_f32_e32 v43, v41
	v_add_f32_e32 v40, v99, v40
	v_add_f32_e32 v40, v151, v40
	v_cvt_pk_bf16_f32 v41, v46, v47
	v_add_f32_e32 v160, v43, v40
	v_cvt_pk_bf16_f32 v40, v44, v45
	v_cvt_pk_bf16_f32 v42, v105, v99
	v_cvt_pk_bf16_f32 v43, v151, v43
	s_waitcnt lgkmcnt(7)
	s_nop 0
	v_mfma_f32_16x16x32_bf16 v[44:47], v[64:67], v[40:43], v[52:55]
	s_waitcnt lgkmcnt(6)
	v_mfma_f32_16x16x32_bf16 v[52:55], v[170:173], v[40:43], v[60:63]
	s_waitcnt lgkmcnt(5)
	v_mfma_f32_16x16x32_bf16 v[60:63], v[182:185], v[40:43], v[68:71]
	s_waitcnt lgkmcnt(4)
	v_mfma_f32_16x16x32_bf16 v[40:43], v[186:189], v[40:43], v[48:51]
	s_nop 2
	ds_read_b128 v[48:51], v139 offset:32768
	ds_read_b128 v[64:67], v139 offset:40960
	ds_read_b128 v[68:71], v139 offset:49152
	ds_read_b128 v[170:173], v139 offset:57344
	v_fma_f32 v36, v36, s67, -v97
	v_exp_f32_e32 v36, v36
	v_fma_f32 v37, v37, s67, -v97
	v_exp_f32_e32 v37, v37
	v_fma_f32 v38, v38, s67, -v97
	v_exp_f32_e32 v38, v38
	v_fma_f32 v39, v39, s67, -v97
	v_exp_f32_e32 v39, v39
	v_fma_f32 v32, v32, s67, -v97
	v_add_f32_e32 v99, v36, v160
	v_exp_f32_e32 v105, v32
	v_add_f32_e32 v99, v37, v99
	v_add_f32_e32 v99, v38, v99
	v_add_f32_e32 v99, v39, v99
	v_fma_f32 v33, v33, s67, -v97
	v_add_f32_e32 v32, v105, v99
	v_exp_f32_e32 v99, v33
	v_fma_f32 v33, v34, s67, -v97
	v_exp_f32_e32 v151, v33
	v_fma_f32 v33, v35, s67, -v97
	v_exp_f32_e32 v35, v33
	v_add_f32_e32 v32, v99, v32
	v_add_f32_e32 v32, v151, v32
	v_cvt_pk_bf16_f32 v33, v38, v39
	v_add_f32_e32 v160, v35, v32
	v_cvt_pk_bf16_f32 v32, v36, v37
	v_cvt_pk_bf16_f32 v34, v105, v99
	v_cvt_pk_bf16_f32 v35, v151, v35
	s_waitcnt lgkmcnt(7)
	s_nop 0
	v_mfma_f32_16x16x32_bf16 v[36:39], v[56:59], v[32:35], v[44:47]
	s_waitcnt lgkmcnt(6)
	v_mfma_f32_16x16x32_bf16 v[44:47], v[152:155], v[32:35], v[52:55]
	s_waitcnt lgkmcnt(5)
	v_mfma_f32_16x16x32_bf16 v[52:55], v[174:177], v[32:35], v[60:63]
	s_waitcnt lgkmcnt(4)
	v_mfma_f32_16x16x32_bf16 v[32:35], v[178:181], v[32:35], v[40:43]
	s_nop 2
	ds_read_b128 v[40:43], v140 offset:32768
	ds_read_b128 v[56:59], v140 offset:40960
	ds_read_b128 v[60:63], v140 offset:49152
	ds_read_b128 v[152:155], v140 offset:57344
	v_fma_f32 v28, v28, s67, -v97
	v_exp_f32_e32 v28, v28
	v_fma_f32 v29, v29, s67, -v97
	v_exp_f32_e32 v29, v29
	v_fma_f32 v30, v30, s67, -v97
	v_exp_f32_e32 v30, v30
	v_fma_f32 v31, v31, s67, -v97
	v_exp_f32_e32 v31, v31
	v_fma_f32 v24, v24, s67, -v97
	v_add_f32_e32 v99, v28, v160
	v_exp_f32_e32 v105, v24
	v_add_f32_e32 v99, v29, v99
	v_add_f32_e32 v99, v30, v99
	v_add_f32_e32 v99, v31, v99
	v_fma_f32 v25, v25, s67, -v97
	v_add_f32_e32 v24, v105, v99
	v_exp_f32_e32 v99, v25
	v_fma_f32 v25, v26, s67, -v97
	v_exp_f32_e32 v151, v25
	v_fma_f32 v25, v27, s67, -v97
	v_exp_f32_e32 v27, v25
	v_add_f32_e32 v24, v99, v24
	v_add_f32_e32 v24, v151, v24
	v_cvt_pk_bf16_f32 v25, v30, v31
	v_add_f32_e32 v160, v27, v24
	v_cvt_pk_bf16_f32 v24, v28, v29
	v_cvt_pk_bf16_f32 v26, v105, v99
	v_cvt_pk_bf16_f32 v27, v151, v27
	s_waitcnt lgkmcnt(7)
	s_nop 0
	v_mfma_f32_16x16x32_bf16 v[28:31], v[48:51], v[24:27], v[36:39]
	s_waitcnt lgkmcnt(6)
	v_mfma_f32_16x16x32_bf16 v[36:39], v[64:67], v[24:27], v[44:47]
	s_waitcnt lgkmcnt(5)
	v_mfma_f32_16x16x32_bf16 v[44:47], v[68:71], v[24:27], v[52:55]
	s_waitcnt lgkmcnt(4)
	v_mfma_f32_16x16x32_bf16 v[24:27], v[170:173], v[24:27], v[32:35]
	s_nop 2
	ds_read_b128 v[32:35], v141 offset:32768
	ds_read_b128 v[48:51], v141 offset:40960
	ds_read_b128 v[52:55], v141 offset:49152
	ds_read_b128 v[64:67], v141 offset:57344
	v_fma_f32 v20, v20, s67, -v97
	v_exp_f32_e32 v20, v20
	v_fma_f32 v21, v21, s67, -v97
	v_exp_f32_e32 v21, v21
	v_fma_f32 v22, v22, s67, -v97
	v_exp_f32_e32 v22, v22
	v_fma_f32 v23, v23, s67, -v97
	v_exp_f32_e32 v23, v23
	v_fma_f32 v16, v16, s67, -v97
	v_add_f32_e32 v68, v20, v160
	v_exp_f32_e32 v69, v16
	v_add_f32_e32 v68, v21, v68
	v_add_f32_e32 v68, v22, v68
	v_add_f32_e32 v68, v23, v68
	v_fma_f32 v17, v17, s67, -v97
	v_add_f32_e32 v16, v69, v68
	v_exp_f32_e32 v68, v17
	v_fma_f32 v17, v18, s67, -v97
	v_exp_f32_e32 v70, v17
	v_fma_f32 v17, v19, s67, -v97
	v_exp_f32_e32 v19, v17
	v_add_f32_e32 v16, v68, v16
	v_add_f32_e32 v16, v70, v16
	v_cvt_pk_bf16_f32 v17, v22, v23
	v_add_f32_e32 v71, v19, v16
	v_cvt_pk_bf16_f32 v16, v20, v21
	v_cvt_pk_bf16_f32 v18, v69, v68
	v_cvt_pk_bf16_f32 v19, v70, v19
	s_waitcnt lgkmcnt(7)
	s_nop 0
	v_mfma_f32_16x16x32_bf16 v[20:23], v[40:43], v[16:19], v[28:31]
	s_waitcnt lgkmcnt(6)
	v_mfma_f32_16x16x32_bf16 v[36:39], v[56:59], v[16:19], v[36:39]
	s_waitcnt lgkmcnt(5)
	v_mfma_f32_16x16x32_bf16 v[40:43], v[60:63], v[16:19], v[44:47]
	s_waitcnt lgkmcnt(4)
	v_mfma_f32_16x16x32_bf16 v[24:27], v[152:155], v[16:19], v[24:27]
	v_fma_f32 v12, v12, s67, -v97
	v_exp_f32_e32 v12, v12
	v_fma_f32 v13, v13, s67, -v97
	v_exp_f32_e32 v13, v13
	v_fma_f32 v14, v14, s67, -v97
	v_exp_f32_e32 v14, v14
	v_fma_f32 v15, v15, s67, -v97
	v_exp_f32_e32 v15, v15
	v_fma_f32 v8, v8, s67, -v97
	v_add_f32_e32 v16, v12, v71
	v_exp_f32_e32 v8, v8
	v_fma_f32 v9, v9, s67, -v97
	v_add_f32_e32 v16, v13, v16
	v_exp_f32_e32 v9, v9
	v_fma_f32 v10, v10, s67, -v97
	v_fma_f32 v11, v11, s67, -v97
	v_add_f32_e32 v16, v14, v16
	v_exp_f32_e32 v10, v10
	v_exp_f32_e32 v11, v11
	v_add_f32_e32 v16, v15, v16
	v_add_f32_e32 v16, v8, v16
	v_add_f32_e32 v16, v9, v16
	v_add_f32_e32 v16, v10, v16
	v_cvt_pk_bf16_f32 v44, v12, v13
	v_cvt_pk_bf16_f32 v45, v14, v15
	v_cvt_pk_bf16_f32 v46, v8, v9
	v_cvt_pk_bf16_f32 v47, v10, v11
	v_add_f32_e32 v28, v11, v16
	s_waitcnt lgkmcnt(3)
	v_mfma_f32_16x16x32_bf16 v[8:11], v[32:35], v[44:47], v[20:23]
	s_waitcnt lgkmcnt(2)
	v_mfma_f32_16x16x32_bf16 v[12:15], v[48:51], v[44:47], v[36:39]
	s_waitcnt lgkmcnt(1)
	v_mfma_f32_16x16x32_bf16 v[16:19], v[52:55], v[44:47], v[40:43]
	s_waitcnt lgkmcnt(0)
	v_mfma_f32_16x16x32_bf16 v[20:23], v[64:67], v[44:47], v[24:27]
	s_andn2_b64 vcc, exec, s[74:75]
	s_mov_b64 s[68:69], -1
	s_cbranch_vccnz .LBB0_298
	ds_bpermute_b32 v24, v114, v28
	v_ashrrev_i32_e32 v105, 31, v104
	s_waitcnt lgkmcnt(0)
	v_add_f32_e32 v24, v28, v24
	ds_bpermute_b32 v25, v115, v24
	s_waitcnt lgkmcnt(0)
	v_add_f32_e32 v24, v24, v25
	v_div_scale_f32 v25, s[68:69], v24, v24, 1.0
	v_rcp_f32_e32 v26, v25
	s_mov_b64 s[68:69], 0
	v_fma_f32 v27, -v25, v26, 1.0
	v_fmac_f32_e32 v26, v27, v26
	v_div_scale_f32 v27, vcc, 1.0, v24, 1.0
	v_mul_f32_e32 v29, v27, v26
	v_fma_f32 v30, -v25, v29, v27
	v_fmac_f32_e32 v29, v30, v26
	v_fma_f32 v25, -v25, v29, v27
	v_div_fmas_f32 v25, v25, v26, v29
	v_div_fixup_f32 v24, v25, v24, 1.0
	v_lshlrev_b64 v[26:27], 11, v[104:105]
	v_pk_mul_f32 v[30:31], v[8:9], v[24:25] op_sel_hi:[1,0]
	v_pk_mul_f32 v[32:33], v[10:11], v[24:25] op_sel_hi:[1,0]
	v_lshl_add_u64 v[26:27], v[102:103], 0, v[26:27]
	v_cvt_pk_bf16_f32 v30, v30, v31
	v_cvt_pk_bf16_f32 v31, v32, v33
	global_store_dwordx2 v[26:27], v[30:31], off offset:1024
	v_pk_mul_f32 v[30:31], v[12:13], v[24:25] op_sel_hi:[1,0]
	v_pk_mul_f32 v[32:33], v[14:15], v[24:25] op_sel_hi:[1,0]
	v_cvt_pk_bf16_f32 v30, v30, v31
	v_cvt_pk_bf16_f32 v31, v32, v33
	global_store_dwordx2 v[26:27], v[30:31], off offset:1056
	v_pk_mul_f32 v[30:31], v[16:17], v[24:25] op_sel_hi:[1,0]
	v_pk_mul_f32 v[32:33], v[18:19], v[24:25] op_sel_hi:[1,0]
	v_cvt_pk_bf16_f32 v30, v30, v31
	v_cvt_pk_bf16_f32 v31, v32, v33
	global_store_dwordx2 v[26:27], v[30:31], off offset:1088
	v_pk_mul_f32 v[30:31], v[20:21], v[24:25] op_sel_hi:[1,0]
	v_pk_mul_f32 v[24:25], v[22:23], v[24:25] op_sel_hi:[1,0]
	v_cvt_pk_bf16_f32 v30, v30, v31
	v_cvt_pk_bf16_f32 v31, v24, v25
	global_store_dwordx2 v[26:27], v[30:31], off offset:1120
	s_branch .LBB0_298
